# FFN-out sample-row GEMM split into 256 units of 32 rows (one per CU, row group = c&3) instead of 64 units of 128 rows on 64 CUs
# speedup vs baseline: 1.0089x; 1.0089x over previous
; #define LAS __attribute__((address_space(3)))
; __device__ __forceinline__ void small_resid(LAS unsigned char* lds, const bf16_t* A, int K, const bf16_t* Bt, const float* xs_in, float* X, const float* modp, float coef, ...
;     for (int un = c; un < 64; un += G) {
;         f32x4 o[1]; small_core<1>(lds, A, K, Bt + (size_t)(16 * un) * K, Bt, K, o);
;         const int row = threadIdx.x >> 2, col = 16 * un + (threadIdx.x & 3) * 4, b = 16 + (row >> 4);
;         f32x4 bs;
;         if (xs_in) bs = *(const f32x4*)(xs_in + (size_t)row * DM + col);
;         else { const u32x2 r_ = *(const u32x2*)(An + (size_t)(NP + row) * DM + col); const f32x4 rg = *(const f32x4*)(rgs + (size_t)b * 1024 + col);
.LBB0_327:
	s_or_b64 exec, exec, s[0:1]
	s_add_u32 s34, s92, 0x1e827c00
	s_addc_u32 s35, s93, 0
	s_add_u32 s28, s92, 0x143c0000
	s_addc_u32 s29, s93, 0
	s_add_u32 s36, s92, 0x2000
	s_addc_u32 s37, s93, 0
	s_add_u32 s38, s92, 0x1e2a8000
	s_addc_u32 s39, s93, 0
	s_cmp_lt_i32 s2, 64
	s_cselect_b64 s[0:1], -1, 0
	v_writelane_b32 v254, s0, 60
	s_cmp_gt_i32 s2, 63
	s_waitcnt lgkmcnt(0)
	v_writelane_b32 v254, s1, 61
	s_barrier
	s_and_b32 s99, s2, 3
	s_mov_b32 s101, 0
	v_lshlrev_b32_e32 v0, 9, v178
	v_and_b32_e32 v32, 0x7f800, v0
	v_mov_b32_e32 v33, 0
	v_or_b32_e32 v2, 16, v179
	v_lshl_add_u32 v2, s99, 1, v2
	v_lshl_add_u64 v[0:1], s[42:43], 0, v[32:33]
	s_mov_b64 s[0:1], 0x4000000
	v_lshl_add_u64 v[34:35], v[0:1], 0, s[0:1]
	s_lshl_b32 s100, s99, 16
	v_lshl_add_u64 v[34:35], v[34:35], 0, s[100:101]
	v_lshlrev_b32_e32 v32, 12, v2
	s_mov_b32 s0, 0x9000
	v_mov_b64_e32 v[0:1], s[36:37]
	v_lshl_add_u64 v[36:37], s[34:35], 0, v[32:33]
	v_mad_u64_u32 v[38:39], s[0:1], v2, s0, v[0:1]
	v_lshl_add_u64 v[40:41], s[38:39], 0, v[32:33]
	v_and_b32_e32 v0, 3, v178
	v_and_b32_e32 v32, 0x3fc, v178
	v_cmp_eq_u32_e64 s[0:1], 0, v0
	v_lshl_add_u64 v[0:1], s[92:93], 0, v[32:33]
	s_mov_b64 s[6:7], 0x1e786400
	v_and_b32_e32 v64, 12, v239
	s_mov_b32 s5, 0
	v_lshl_add_u64 v[42:43], v[0:1], 0, s[6:7]
	s_lshl_b32 s100, s99, 7
	v_lshl_add_u64 v[42:43], v[42:43], 0, s[100:101]
	s_mov_b64 s[6:7], 0x84000
	s_mov_b64 s[8:9], 0x9a000
	v_mbcnt_hi_u32_b32 v65, -1, v161
	s_lshr_b32 s12, s2, 2
	s_branch .LBB0_330

; #define LAS __attribute__((address_space(3)))
; template <int NB>
; __device__ __forceinline__ void small_core(LAS unsigned char* lds, const bf16_t* A, int lda, const bf16_t* B0, const bf16_t* B1, int K, f32x4 (&out)[NB]) {
;     int tid_ = threadIdx.x; asm volatile("" : "+v"(tid_));
;     const int tid = tid_, lane = tid & 63, w = __builtin_amdgcn_readfirstlane(tid >> 6), fr = lane & 15, fq = lane >> 4;
;     f32x4 acc[NB][8];
; #pragma unroll
;     for (int nb = 0; nb < NB; ++nb)
; #pragma unroll
;         for (int mb = 0; mb < 8; ++mb) acc[nb][mb] = (f32x4){0.f, 0.f, 0.f, 0.f};
;     const bf16_t* ap = A + (size_t)fr * lda + 8 * fq;
;     const bf16_t* bp0 = B0 + (size_t)fr * K + 8 * fq;
;     const bf16_t* bp1 = B1 + (size_t)fr * K + 8 * fq;
;     const int nsteps = K >> 5;
;     int st = w;
;     for (; st + 8 < nsteps; st += 16) {
;         const int k = st * 32, k2 = k + 256;
;         bf16x8 b[NB], b2[NB]; b[0] = *(const bf16x8*)(bp0 + k); b2[0] = *(const bf16x8*)(bp0 + k2);
;         if (NB == 2) { b[NB - 1] = *(const bf16x8*)(bp1 + k); b2[NB - 1] = *(const bf16x8*)(bp1 + k2); }
;         bf16x8 a[8], a2[8];
; #pragma unroll
;         for (int mb = 0; mb < 8; ++mb) { a[mb] = *(const bf16x8*)(ap + (size_t)(16 * mb) * lda + k); a2[mb] = *(const bf16x8*)(ap + (size_t)(16 * mb) * lda + k2); }
; #pragma unroll
;         for (int mb = 0; mb < 8; ++mb)
; #pragma unroll
;             for (int nb = 0; nb < NB; ++nb) { acc[nb][mb] = __builtin_amdgcn_mfma_f32_16x16x32_bf16(b[nb], a[mb], acc[nb][mb], 0, 0, 0);
;                 acc[nb][mb] = __builtin_amdgcn_mfma_f32_16x16x32_bf16(b2[nb], a2[mb], acc[nb][mb], 0, 0, 0); }
;     }
.LBB0_330:
	v_mov_b32_e32 v66, v178
	s_lshl_b32 s13, s12, 4
	v_and_b32_e32 v67, 15, v66
	s_mul_i32 s4, s12, 0x16000
	v_readlane_b32 s3, v254, 30
	v_mul_u32_u24_e32 v0, 0xb00, v67
	s_mul_hi_i32 s11, s13, 0x1600
	s_add_u32 s10, s3, s4
	v_readlane_b32 s3, v254, 31
	v_bfe_u32 v2, v66, 4, 2
	v_lshlrev_b32_e32 v32, 1, v0
	s_addc_u32 s11, s3, s11
	v_readfirstlane_b32 s4, v66
	s_waitcnt lgkmcnt(0)
	v_lshl_add_u64 v[0:1], s[28:29], 0, v[32:33]
	v_lshlrev_b32_e32 v44, 4, v2
	v_mov_b32_e32 v45, v33
	s_ashr_i32 s16, s4, 6
	v_lshl_add_u64 v[46:47], v[0:1], 0, v[44:45]
	s_mul_i32 s100, s99, 0x2c000
	v_lshl_add_u64 v[46:47], v[46:47], 0, s[100:101]
	v_lshl_add_u64 v[0:1], s[10:11], 0, v[32:33]
	v_lshl_add_u64 v[48:49], v[0:1], 0, v[44:45]
	s_cmpk_gt_i32 s16, 0x4f
	v_mov_b32_e32 v11, 0
	v_mov_b32_e32 v10, 0
	v_mov_b32_e32 v9, 0
	v_mov_b32_e32 v8, 0
	v_mov_b32_e32 v3, 0
	v_mov_b32_e32 v2, 0
	v_mov_b32_e32 v1, 0
	v_mov_b32_e32 v0, 0
	v_mov_b32_e32 v7, 0
	v_mov_b32_e32 v6, 0
	v_mov_b32_e32 v5, 0
	v_mov_b32_e32 v4, 0
	v_mov_b32_e32 v15, 0
	v_mov_b32_e32 v14, 0
	v_mov_b32_e32 v13, 0
	v_mov_b32_e32 v12, 0
	v_mov_b32_e32 v19, 0
	v_mov_b32_e32 v18, 0
	v_mov_b32_e32 v17, 0
	v_mov_b32_e32 v16, 0
	v_mov_b32_e32 v23, 0
	v_mov_b32_e32 v22, 0
	v_mov_b32_e32 v21, 0
	v_mov_b32_e32 v20, 0
	v_mov_b32_e32 v27, 0
	v_mov_b32_e32 v26, 0
	v_mov_b32_e32 v25, 0
	v_mov_b32_e32 v24, 0
	v_mov_b32_e32 v31, 0
	v_mov_b32_e32 v30, 0
	v_mov_b32_e32 v29, 0
	v_mov_b32_e32 v28, 0
	s_mov_b32 s4, s16
	s_cbranch_scc1 .LBB0_333
	s_mov_b64 s[10:11], 0x16000
	v_lshl_add_u64 v[50:51], v[46:47], 0, s[10:11]
	s_mov_b64 s[10:11], 0x2c000
	v_lshl_add_u64 v[52:53], v[46:47], 0, s[10:11]
	s_mov_b64 s[10:11], 0x42000
	v_lshl_add_u64 v[54:55], v[46:47], 0, s[10:11]
	s_mov_b64 s[10:11], 0x58000
	v_lshl_add_u64 v[56:57], v[46:47], 0, s[10:11]
	s_mov_b64 s[10:11], 0x6e000
	v_mov_b32_e32 v28, 0
	v_lshl_add_u64 v[58:59], v[46:47], 0, s[10:11]
	v_lshl_add_u64 v[60:61], v[46:47], 0, s[6:7]
	v_lshl_add_u64 v[62:63], v[46:47], 0, s[8:9]
	s_lshl_b32 s10, s16, 5
	s_mov_b32 s4, s16
	v_mov_b32_e32 v29, v28
	v_mov_b32_e32 v30, v28
	v_mov_b32_e32 v31, v28
	v_mov_b32_e32 v24, v28
	v_mov_b32_e32 v25, v28
	v_mov_b32_e32 v26, v28
	v_mov_b32_e32 v27, v28
	v_mov_b32_e32 v20, v28
	v_mov_b32_e32 v21, v28
	v_mov_b32_e32 v22, v28
	v_mov_b32_e32 v23, v28
	v_mov_b32_e32 v16, v28
	v_mov_b32_e32 v17, v28
	v_mov_b32_e32 v18, v28
	v_mov_b32_e32 v19, v28
	v_mov_b32_e32 v12, v28
	v_mov_b32_e32 v13, v28
	v_mov_b32_e32 v14, v28
	v_mov_b32_e32 v15, v28
	v_mov_b32_e32 v4, v28
	v_mov_b32_e32 v5, v28
	v_mov_b32_e32 v6, v28
	v_mov_b32_e32 v7, v28
	v_mov_b32_e32 v0, v28
	v_mov_b32_e32 v1, v28
	v_mov_b32_e32 v2, v28
	v_mov_b32_e32 v3, v28
	v_mov_b32_e32 v8, v28
	v_mov_b32_e32 v9, v28
	v_mov_b32_e32 v10, v28
	v_mov_b32_e32 v11, v28
.LBB0_332:
	s_ashr_i32 s11, s10, 31
	s_lshl_b64 s[20:21], s[10:11], 1
	v_lshl_add_u64 v[80:81], v[48:49], 0, s[20:21]
	v_lshl_add_u64 v[82:83], v[46:47], 0, s[20:21]
	v_lshl_add_u64 v[84:85], v[50:51], 0, s[20:21]
	global_load_dwordx4 v[104:107], v[80:81], off
	global_load_dwordx4 v[108:111], v[82:83], off
	global_load_dwordx4 v[112:115], v[84:85], off
	v_lshl_add_u64 v[86:87], v[52:53], 0, s[20:21]
	v_lshl_add_u64 v[88:89], v[54:55], 0, s[20:21]
	v_lshl_add_u64 v[90:91], v[56:57], 0, s[20:21]
	v_lshl_add_u64 v[92:93], v[58:59], 0, s[20:21]
	v_lshl_add_u64 v[94:95], v[60:61], 0, s[20:21]
	v_lshl_add_u64 v[96:97], v[62:63], 0, s[20:21]
	s_mov_b32 s11, s4
	s_add_i32 s4, s4, 16
	s_addk_i32 s10, 0x200
	s_cmp_lt_i32 s11, 64
	global_load_dwordx4 v[154:157], v[80:81], off offset:512
	global_load_dwordx4 v[162:165], v[82:83], off offset:512
	global_load_dwordx4 v[172:175], v[84:85], off offset:512
	s_waitcnt vmcnt(0)
	v_mfma_f32_16x16x32_bf16 v[28:31], v[104:107], v[108:111], v[28:31]
	v_mfma_f32_16x16x32_bf16 v[24:27], v[104:107], v[112:115], v[24:27]
	v_mfma_f32_16x16x32_bf16 v[28:31], v[154:157], v[162:165], v[28:31]
	v_mfma_f32_16x16x32_bf16 v[24:27], v[154:157], v[172:175], v[24:27]
	s_cbranch_scc1 .LBB0_332
; #define LAS __attribute__((address_space(3)))
; template <int NB>
; __device__ __forceinline__ void small_core(LAS unsigned char* lds, const bf16_t* A, int lda, const bf16_t* B0, const bf16_t* B1, int K, f32x4 (&out)[NB]) {
;     ...
;     if (st < nsteps) {
;         const int k = st * 32;
;         bf16x8 b[NB]; b[0] = *(const bf16x8*)(bp0 + k); if (NB == 2) b[NB - 1] = *(const bf16x8*)(bp1 + k);
;         bf16x8 a[8];
; #pragma unroll
;         for (int mb = 0; mb < 8; ++mb) a[mb] = *(const bf16x8*)(ap + (size_t)(16 * mb) * lda + k);
; #pragma unroll
;         for (int mb = 0; mb < 8; ++mb)
; #pragma unroll
;             for (int nb = 0; nb < NB; ++nb) acc[nb][mb] = __builtin_amdgcn_mfma_f32_16x16x32_bf16(b[nb], a[mb], acc[nb][mb], 0, 0, 0);
;     }
;     LAS float* red = (LAS float*)lds;
;     __syncthreads();
; #pragma unroll
;     for (int nb = 0; nb < NB; ++nb)
; #pragma unroll
;         for (int mb = 0; mb < 8; ++mb) *(LAS f32x4*)(red + ((w * 128 + 16 * mb + fr) * (16 * NB) + nb * 16 + 4 * fq)) = acc[nb][mb];
;     __syncthreads();
;     const int row = tid >> 2, c4 = (tid & 3) * 4;
; #pragma unroll
;     for (int nb = 0; nb < NB; ++nb) { f32x4 s = (f32x4){0.f, 0.f, 0.f, 0.f};
; #pragma unroll
;         for (int w8 = 0; w8 < 8; ++w8) s += *(const LAS f32x4*)(red + ((w8 * 128 + row) * (16 * NB) + nb * 16 + c4));
;         out[nb] = s; }
;     __syncthreads();
; }
; __device__ __forceinline__ void small_swiglu(LAS unsigned char* lds, const bf16_t* A, const bf16_t* Bt, bf16_t* ACT, const float* ssq, const float* biasw, int G, int c) {
;     for (int un = c; un < DFF / 16; un += G) {
;         const int j0 = 16 * un, rg = (j0 >> 7) * 256 + (j0 & 127);
;         f32x4 o[2]; small_core<2>(lds, A, 1024, Bt + (size_t)rg * 1024, Bt + (size_t)(rg + 128) * 1024, 1024, o);
;         const int row = threadIdx.x >> 2, c4 = (threadIdx.x & 3) * 4, b = 16 + (row >> 4);
;         const float rstd = __builtin_amdgcn_rsqf(ssq[NP + row] * (1.0f / 1024.0f) + EPS);
;         const f32x4 g = o[0] * rstd + *(const f32x4*)(biasw + (size_t)b * 5632 + rg + c4), uu = o[1] * rstd + *(const f32x4*)(biasw + (size_t)b * 5632 + rg + 128 + c4);
;         u32x2 wv; wv.x = pk2(silu_f(g[0]) * uu[0], silu_f(g[1]) * uu[1]); wv.y = pk2(silu_f(g[2]) * uu[2], silu_f(g[3]) * uu[3]);
;         *(u32x2*)(ACT + (size_t)(NP + row) * DFF + j0 + c4) = wv;
;     }
; }
.LBB0_333:
	s_cmpk_gt_u32 s4, 0x57
	s_cbranch_scc1 .LBB0_335
	s_lshl_b32 s4, s4, 6
	v_lshl_add_u64 v[48:49], v[48:49], 0, s[4:5]
	global_load_dwordx4 v[104:107], v[48:49], off
	v_lshl_add_u64 v[46:47], v[46:47], 0, s[4:5]
	global_load_dwordx4 v[108:111], v[46:47], off
	v_add_co_u32_e32 v56, vcc, 0x16000, v46
	v_addc_co_u32_e32 v57, vcc, 0, v47, vcc
	v_add_co_u32_e32 v60, vcc, 0x2c000, v46
	s_nop 1
	v_addc_co_u32_e32 v61, vcc, 0, v47, vcc
	v_add_co_u32_e32 v68, vcc, 0x42000, v46
	global_load_dwordx4 v[112:115], v[56:57], off
	s_nop 0
	v_addc_co_u32_e32 v69, vcc, 0, v47, vcc
	v_add_co_u32_e32 v72, vcc, 0x58000, v46
	v_addc_co_u32_e32 v73, vcc, 0, v47, vcc
	v_add_co_u32_e32 v72, vcc, 0x6e000, v46
	s_nop 0
	v_addc_co_u32_e32 v73, vcc, 0, v47, vcc
	v_add_co_u32_e32 v60, vcc, 0x84000, v46
	s_nop 0
	v_addc_co_u32_e32 v61, vcc, 0, v47, vcc
	v_add_co_u32_e32 v46, vcc, 0x9a000, v46
	s_nop 0
	v_addc_co_u32_e32 v47, vcc, 0, v47, vcc
	s_waitcnt vmcnt(0)
	v_mfma_f32_16x16x32_bf16 v[28:31], v[104:107], v[108:111], v[28:31]
	v_mfma_f32_16x16x32_bf16 v[24:27], v[104:107], v[112:115], v[24:27]
.LBB0_335:
	s_lshl_b32 s4, s16, 13
	v_lshlrev_b32_e32 v32, 6, v67
	s_add_i32 s4, s4, 0
	v_add3_u32 v32, s4, v44, v32
	s_barrier
	ds_write_b128 v32, v[28:31]
	ds_write_b128 v32, v[24:27] offset:1024
	ds_write_b128 v32, v[20:23] offset:2048
	ds_write_b128 v32, v[16:19] offset:3072
	ds_write_b128 v32, v[12:15] offset:4096
	ds_write_b128 v32, v[4:7] offset:5120
	ds_write_b128 v32, v[0:3] offset:6144
	ds_write_b128 v32, v[8:11] offset:7168
	v_lshlrev_b32_e32 v0, 4, v66
	v_and_b32_e32 v1, 48, v0
	v_and_b32_e32 v0, 0xffffffc0, v0
	v_add3_u32 v8, 0, v1, v0
	s_waitcnt lgkmcnt(0)
	s_barrier
	ds_read_b128 v[0:3], v8
	s_waitcnt lgkmcnt(0)
	v_pk_add_f32 v[4:5], v[2:3], 0 op_sel_hi:[1,0]
	v_pk_add_f32 v[6:7], v[0:1], 0 op_sel_hi:[1,0]
	ds_read_b128 v[0:3], v8 offset:8192
	s_waitcnt lgkmcnt(0)
	v_pk_add_f32 v[4:5], v[4:5], v[2:3]
	v_pk_add_f32 v[6:7], v[6:7], v[0:1]
	ds_read_b128 v[0:3], v8 offset:16384
	s_waitcnt lgkmcnt(0)
	v_pk_add_f32 v[4:5], v[4:5], v[2:3]
	v_pk_add_f32 v[6:7], v[6:7], v[0:1]
	ds_read_b128 v[0:3], v8 offset:24576
	s_waitcnt lgkmcnt(0)
	v_pk_add_f32 v[4:5], v[4:5], v[2:3]
	v_pk_add_f32 v[6:7], v[6:7], v[0:1]
	ds_read_b128 v[0:3], v8 offset:32768
	s_waitcnt lgkmcnt(0)
	v_pk_add_f32 v[4:5], v[4:5], v[2:3]
	v_pk_add_f32 v[6:7], v[6:7], v[0:1]
	ds_read_b128 v[0:3], v8 offset:40960
	s_waitcnt lgkmcnt(0)
	v_pk_add_f32 v[4:5], v[4:5], v[2:3]
	v_pk_add_f32 v[6:7], v[6:7], v[0:1]
	ds_read_b128 v[0:3], v8 offset:49152
	s_waitcnt lgkmcnt(0)
	v_pk_add_f32 v[4:5], v[4:5], v[2:3]
	v_pk_add_f32 v[6:7], v[6:7], v[0:1]
	ds_read_b128 v[0:3], v8 offset:57344
	s_waitcnt lgkmcnt(0)
	s_barrier
	v_readfirstlane_b32 s100, v178
	s_cmpk_gt_u32 s100, 0x7f
	s_cbranch_scc1 .LBB0_329
	v_pk_add_f32 v[6:7], v[6:7], v[0:1]
	v_or_b32_e32 v0, s13, v64
	v_ashrrev_i32_e32 v1, 31, v0
	v_lshl_add_u64 v[8:9], v[0:1], 1, v[34:35]
	v_lshlrev_b64 v[12:13], 2, v[0:1]
	global_load_dwordx2 v[10:11], v[8:9], off
	v_lshl_add_u64 v[0:1], v[36:37], 0, v[12:13]
	v_pk_add_f32 v[4:5], v[4:5], v[2:3]
	global_load_dwordx4 v[0:3], v[0:1], off
	s_waitcnt vmcnt(1)
	v_lshlrev_b32_e32 v14, 16, v10
	v_and_b32_e32 v15, 0xffff0000, v10
	v_lshlrev_b32_e32 v10, 16, v11
	v_and_b32_e32 v11, 0xffff0000, v11
	s_waitcnt vmcnt(0)
	v_pk_mul_f32 v[14:15], v[0:1], v[14:15]
	v_lshl_add_u64 v[0:1], v[38:39], 0, v[12:13]
	v_pk_mul_f32 v[10:11], v[2:3], v[10:11]
	global_load_dwordx4 v[0:3], v[0:1], off
	s_waitcnt vmcnt(0)
	v_pk_mul_f32 v[0:1], v[0:1], 0.5 op_sel_hi:[1,0]
	v_pk_mul_f32 v[2:3], v[2:3], 0.5 op_sel_hi:[1,0]
	v_pk_fma_f32 v[6:7], v[6:7], v[0:1], v[14:15]
	v_lshl_add_u64 v[0:1], v[40:41], 0, v[12:13]
	v_pk_fma_f32 v[4:5], v[4:5], v[2:3], v[10:11]
	global_load_dwordx4 v[0:3], v[0:1], off
	v_mul_f32_e32 v10, v7, v7
	v_fmac_f32_e32 v10, v6, v6
	v_fmac_f32_e32 v10, v4, v4
	v_fmac_f32_e32 v10, v5, v5
	s_waitcnt vmcnt(0)
	v_pk_mul_f32 v[2:3], v[2:3], v[4:5]
	v_pk_mul_f32 v[0:1], v[0:1], v[6:7]
	s_nop 0
	v_cvt_pk_bf16_f32 v0, v0, v1
	v_cvt_pk_bf16_f32 v1, v2, v3
	global_store_dwordx2 v[8:9], v[0:1], off
	v_and_b32_e32 v1, 64, v65
	v_xor_b32_e32 v0, 1, v65
	v_add_u32_e32 v1, 64, v1
	v_cmp_lt_i32_e32 vcc, v0, v1
	v_xor_b32_e32 v2, 2, v65
	s_nop 0
	v_cndmask_b32_e32 v0, v65, v0, vcc
	v_lshlrev_b32_e32 v0, 2, v0
	ds_bpermute_b32 v0, v0, v10
	v_cmp_lt_i32_e32 vcc, v2, v1
	s_waitcnt lgkmcnt(0)
	v_add_f32_e32 v0, v10, v0
	v_cndmask_b32_e32 v1, v65, v2, vcc
	v_lshlrev_b32_e32 v1, 2, v1
	ds_bpermute_b32 v1, v1, v0
	s_and_saveexec_b64 s[10:11], s[0:1]
	s_cbranch_execz .LBB0_329
	s_waitcnt lgkmcnt(0)
	v_add_f32_e32 v0, v0, v1
	global_atomic_add_f32 v[42:43], v0, off
	s_branch .LBB0_329

; #define LAS __attribute__((address_space(3)))
; __device__ __forceinline__ void small_resid(LAS unsigned char* lds, const bf16_t* A, int K, const bf16_t* Bt, const float* xs_in, float* X, const float* modp, float coef, ...
;     for (int un = c; un < 64; un += G) {
;         f32x4 o[1]; small_core<1>(lds, A, K, Bt + (size_t)(16 * un) * K, Bt, K, o);
;         const int row = threadIdx.x >> 2, col = 16 * un + (threadIdx.x & 3) * 4, b = 16 + (row >> 4);
;         f32x4 bs;
;         if (xs_in) bs = *(const f32x4*)(xs_in + (size_t)row * DM + col);
;         else { const u32x2 r_ = *(const u32x2*)(An + (size_t)(NP + row) * DM + col); const f32x4 rg = *(const f32x4*)(rgs + (size_t)b * 1024 + col);
.LBB0_1056:
	s_or_b64 exec, exec, s[0:1]
	s_add_u32 s3, s92, 0x3330000
	s_addc_u32 s25, s93, 0
	s_add_u32 s22, s92, 0x8000
	s_addc_u32 s23, s93, 0
	s_add_u32 s34, s92, 0x1e2d8000
	s_addc_u32 s35, s93, 0
	s_add_u32 s36, s92, 0x1e857c00
	s_addc_u32 s37, s93, 0
	s_and_b64 vcc, exec, s[6:7]
	s_waitcnt lgkmcnt(0)
	s_barrier
	s_and_b32 s99, s2, 3
	s_mov_b32 s101, 0
	v_lshlrev_b32_e32 v0, 9, v178
	v_and_b32_e32 v32, 0x7f800, v0
	v_mov_b32_e32 v33, 0
	v_or_b32_e32 v2, 16, v179
	v_lshl_add_u32 v2, s99, 1, v2
	v_lshl_add_u64 v[0:1], s[42:43], 0, v[32:33]
	s_mov_b64 s[0:1], 0x4000000
	v_lshl_add_u64 v[34:35], v[0:1], 0, s[0:1]
	s_lshl_b32 s100, s99, 16
	v_lshl_add_u64 v[34:35], v[34:35], 0, s[100:101]
	v_lshlrev_b32_e32 v32, 12, v2
	s_mov_b32 s0, 0x9000
	v_mov_b64_e32 v[0:1], s[22:23]
	v_lshl_add_u64 v[36:37], s[36:37], 0, v[32:33]
	v_mad_u64_u32 v[38:39], s[0:1], v2, s0, v[0:1]
	v_lshl_add_u64 v[40:41], s[34:35], 0, v[32:33]
	v_and_b32_e32 v0, 3, v178
	v_and_b32_e32 v32, 0x3fc, v178
	v_cmp_eq_u32_e64 s[0:1], 0, v0
	v_lshl_add_u64 v[0:1], s[92:93], 0, v[32:33]
	s_mov_b64 s[12:13], 0x1e7c6c00
	v_readlane_b32 s58, v255, 2
	s_waitcnt vmcnt(1)
	v_and_b32_e32 v64, 12, v239
	s_mov_b32 s5, 0
	v_lshl_add_u64 v[42:43], v[0:1], 0, s[12:13]
	s_lshl_b32 s100, s99, 7
	v_lshl_add_u64 v[42:43], v[42:43], 0, s[100:101]
	s_mov_b64 s[12:13], 0x16000
	s_mov_b64 s[14:15], 0x2c000
	s_mov_b64 s[16:17], 0x42000
	s_mov_b64 s[18:19], 0x58000
	s_mov_b64 s[20:21], 0x6e000
	s_mov_b64 s[38:39], 0x84000
	s_mov_b64 s[40:41], 0x9a000
	s_lshr_b32 s33, s2, 2
	v_readlane_b32 s59, v255, 3
	s_branch .LBB0_1059

; #define LAS __attribute__((address_space(3)))
; template <int NB>
; __device__ __forceinline__ void small_core(LAS unsigned char* lds, const bf16_t* A, int lda, const bf16_t* B0, const bf16_t* B1, int K, f32x4 (&out)[NB]) {
;     int tid_ = threadIdx.x; asm volatile("" : "+v"(tid_));
;     const int tid = tid_, lane = tid & 63, w = __builtin_amdgcn_readfirstlane(tid >> 6), fr = lane & 15, fq = lane >> 4;
;     f32x4 acc[NB][8];
; #pragma unroll
;     for (int nb = 0; nb < NB; ++nb)
; #pragma unroll
;         for (int mb = 0; mb < 8; ++mb) acc[nb][mb] = (f32x4){0.f, 0.f, 0.f, 0.f};
;     const bf16_t* ap = A + (size_t)fr * lda + 8 * fq;
;     const bf16_t* bp0 = B0 + (size_t)fr * K + 8 * fq;
;     const bf16_t* bp1 = B1 + (size_t)fr * K + 8 * fq;
;     const int nsteps = K >> 5;
;     int st = w;
;     for (; st + 8 < nsteps; st += 16) {
;         const int k = st * 32, k2 = k + 256;
;         bf16x8 b[NB], b2[NB]; b[0] = *(const bf16x8*)(bp0 + k); b2[0] = *(const bf16x8*)(bp0 + k2);
;         if (NB == 2) { b[NB - 1] = *(const bf16x8*)(bp1 + k); b2[NB - 1] = *(const bf16x8*)(bp1 + k2); }
;         bf16x8 a[8], a2[8];
; #pragma unroll
;         for (int mb = 0; mb < 8; ++mb) { a[mb] = *(const bf16x8*)(ap + (size_t)(16 * mb) * lda + k); a2[mb] = *(const bf16x8*)(ap + (size_t)(16 * mb) * lda + k2); }
; #pragma unroll
;         for (int mb = 0; mb < 8; ++mb)
; #pragma unroll
;             for (int nb = 0; nb < NB; ++nb) { acc[nb][mb] = __builtin_amdgcn_mfma_f32_16x16x32_bf16(b[nb], a[mb], acc[nb][mb], 0, 0, 0);
;                 acc[nb][mb] = __builtin_amdgcn_mfma_f32_16x16x32_bf16(b2[nb], a2[mb], acc[nb][mb], 0, 0, 0); }
;     }
.LBB0_1059:
	v_mov_b32_e32 v65, v178
	s_lshl_b32 s46, s33, 4
	v_and_b32_e32 v66, 15, v65
	s_mul_i32 s4, s33, 0x16000
	v_mul_u32_u24_e32 v0, 0xb00, v66
	s_mul_hi_i32 s47, s46, 0x1600
	s_add_u32 s52, s3, s4
	v_bfe_u32 v2, v65, 4, 2
	v_lshlrev_b32_e32 v32, 1, v0
	s_addc_u32 s53, s25, s47
	v_readfirstlane_b32 s4, v65
	s_waitcnt lgkmcnt(0)
	v_lshl_add_u64 v[0:1], s[58:59], 0, v[32:33]
	v_lshlrev_b32_e32 v44, 4, v2
	v_mov_b32_e32 v45, v33
	s_ashr_i32 s47, s4, 6
	v_lshl_add_u64 v[46:47], v[0:1], 0, v[44:45]
	s_mul_i32 s100, s99, 0x2c000
	v_lshl_add_u64 v[46:47], v[46:47], 0, s[100:101]
	v_lshl_add_u64 v[0:1], s[52:53], 0, v[32:33]
	v_lshl_add_u64 v[48:49], v[0:1], 0, v[44:45]
	s_cmpk_gt_i32 s47, 0x4f
	v_mov_b32_e32 v3, 0
	v_mov_b32_e32 v2, 0
	v_mov_b32_e32 v1, 0
	v_mov_b32_e32 v0, 0
	v_mov_b32_e32 v7, 0
	v_mov_b32_e32 v6, 0
	v_mov_b32_e32 v5, 0
	v_mov_b32_e32 v4, 0
	v_mov_b32_e32 v11, 0
	v_mov_b32_e32 v10, 0
	v_mov_b32_e32 v9, 0
	v_mov_b32_e32 v8, 0
	v_mov_b32_e32 v15, 0
	v_mov_b32_e32 v14, 0
	v_mov_b32_e32 v13, 0
	v_mov_b32_e32 v12, 0
	v_mov_b32_e32 v19, 0
	v_mov_b32_e32 v18, 0
	v_mov_b32_e32 v17, 0
	v_mov_b32_e32 v16, 0
	v_mov_b32_e32 v23, 0
	v_mov_b32_e32 v22, 0
	v_mov_b32_e32 v21, 0
	v_mov_b32_e32 v20, 0
	v_mov_b32_e32 v27, 0
	v_mov_b32_e32 v26, 0
	v_mov_b32_e32 v25, 0
	v_mov_b32_e32 v24, 0
	v_mov_b32_e32 v31, 0
	v_mov_b32_e32 v30, 0
	v_mov_b32_e32 v29, 0
	v_mov_b32_e32 v28, 0
	s_mov_b32 s4, s47
	s_cbranch_scc1 .LBB0_1062
	v_mov_b32_e32 v28, 0
	v_lshl_add_u64 v[50:51], v[46:47], 0, s[12:13]
	v_lshl_add_u64 v[52:53], v[46:47], 0, s[14:15]
	v_lshl_add_u64 v[54:55], v[46:47], 0, s[16:17]
	v_lshl_add_u64 v[56:57], v[46:47], 0, s[18:19]
	v_lshl_add_u64 v[58:59], v[46:47], 0, s[20:21]
	s_waitcnt vmcnt(0)
	v_lshl_add_u64 v[60:61], v[46:47], 0, s[38:39]
	v_lshl_add_u64 v[62:63], v[46:47], 0, s[40:41]
	s_lshl_b32 s52, s47, 5
	s_mov_b32 s4, s47
	v_mov_b32_e32 v29, v28
	v_mov_b32_e32 v30, v28
	v_mov_b32_e32 v31, v28
	v_mov_b32_e32 v24, v28
	v_mov_b32_e32 v25, v28
	v_mov_b32_e32 v26, v28
	v_mov_b32_e32 v27, v28
	v_mov_b32_e32 v20, v28
	v_mov_b32_e32 v21, v28
	v_mov_b32_e32 v22, v28
	v_mov_b32_e32 v23, v28
	v_mov_b32_e32 v16, v28
	v_mov_b32_e32 v17, v28
	v_mov_b32_e32 v18, v28
	v_mov_b32_e32 v19, v28
	v_mov_b32_e32 v12, v28
	v_mov_b32_e32 v13, v28
	v_mov_b32_e32 v14, v28
	v_mov_b32_e32 v15, v28
	v_mov_b32_e32 v8, v28
	v_mov_b32_e32 v9, v28
	v_mov_b32_e32 v10, v28
	v_mov_b32_e32 v11, v28
	v_mov_b32_e32 v4, v28
	v_mov_b32_e32 v5, v28
	v_mov_b32_e32 v6, v28
	v_mov_b32_e32 v7, v28
	v_mov_b32_e32 v0, v28
	v_mov_b32_e32 v1, v28
	v_mov_b32_e32 v2, v28
	v_mov_b32_e32 v3, v28
.LBB0_1061:
	s_ashr_i32 s53, s52, 31
	s_lshl_b64 s[56:57], s[52:53], 1
	v_lshl_add_u64 v[100:101], v[48:49], 0, s[56:57]
	v_lshl_add_u64 v[108:109], v[46:47], 0, s[56:57]
	v_lshl_add_u64 v[112:113], v[50:51], 0, s[56:57]
	v_lshl_add_u64 v[114:115], v[52:53], 0, s[56:57]
	v_lshl_add_u64 v[116:117], v[54:55], 0, s[56:57]
	v_lshl_add_u64 v[118:119], v[56:57], 0, s[56:57]
	v_lshl_add_u64 v[120:121], v[58:59], 0, s[56:57]
	v_lshl_add_u64 v[122:123], v[60:61], 0, s[56:57]
	v_lshl_add_u64 v[124:125], v[62:63], 0, s[56:57]
	global_load_dwordx4 v[126:129], v[100:101], off
	global_load_dwordx4 v[130:133], v[108:109], off
	global_load_dwordx4 v[142:145], v[112:113], off
	s_nop 0
	global_load_dwordx4 v[166:169], v[100:101], off offset:512
	s_nop 0
	s_nop 0
	global_load_dwordx4 v[194:197], v[108:109], off offset:512
	s_mov_b32 s53, s4
	s_add_i32 s4, s4, 16
	s_addk_i32 s52, 0x200
	s_cmp_lt_i32 s53, 64
	global_load_dwordx4 v[198:201], v[112:113], off offset:512
	s_waitcnt vmcnt(0)
	v_mfma_f32_16x16x32_bf16 v[28:31], v[126:129], v[130:133], v[28:31]
	v_mfma_f32_16x16x32_bf16 v[24:27], v[126:129], v[142:145], v[24:27]
	v_mfma_f32_16x16x32_bf16 v[28:31], v[166:169], v[194:197], v[28:31]
	v_mfma_f32_16x16x32_bf16 v[24:27], v[166:169], v[198:201], v[24:27]
	s_cbranch_scc1 .LBB0_1061
; #define LAS __attribute__((address_space(3)))
; template <int NB>
; __device__ __forceinline__ void small_core(LAS unsigned char* lds, const bf16_t* A, int lda, const bf16_t* B0, const bf16_t* B1, int K, f32x4 (&out)[NB]) {
;     ...
;     if (st < nsteps) {
;         const int k = st * 32;
;         bf16x8 b[NB]; b[0] = *(const bf16x8*)(bp0 + k); if (NB == 2) b[NB - 1] = *(const bf16x8*)(bp1 + k);
;         bf16x8 a[8];
; #pragma unroll
;         for (int mb = 0; mb < 8; ++mb) a[mb] = *(const bf16x8*)(ap + (size_t)(16 * mb) * lda + k);
; #pragma unroll
;         for (int mb = 0; mb < 8; ++mb)
; #pragma unroll
;             for (int nb = 0; nb < NB; ++nb) acc[nb][mb] = __builtin_amdgcn_mfma_f32_16x16x32_bf16(b[nb], a[mb], acc[nb][mb], 0, 0, 0);
;     }
;     LAS float* red = (LAS float*)lds;
;     __syncthreads();
; #pragma unroll
;     for (int nb = 0; nb < NB; ++nb)
; #pragma unroll
;         for (int mb = 0; mb < 8; ++mb) *(LAS f32x4*)(red + ((w * 128 + 16 * mb + fr) * (16 * NB) + nb * 16 + 4 * fq)) = acc[nb][mb];
;     __syncthreads();
;     const int row = tid >> 2, c4 = (tid & 3) * 4;
; #pragma unroll
;     for (int nb = 0; nb < NB; ++nb) { f32x4 s = (f32x4){0.f, 0.f, 0.f, 0.f};
; #pragma unroll
;         for (int w8 = 0; w8 < 8; ++w8) s += *(const LAS f32x4*)(red + ((w8 * 128 + row) * (16 * NB) + nb * 16 + c4));
;         out[nb] = s; }
;     __syncthreads();
; }
; __device__ __forceinline__ void small_swiglu(LAS unsigned char* lds, const bf16_t* A, const bf16_t* Bt, bf16_t* ACT, const float* ssq, const float* biasw, int G, int c) {
;     for (int un = c; un < DFF / 16; un += G) {
;         const int j0 = 16 * un, rg = (j0 >> 7) * 256 + (j0 & 127);
;         f32x4 o[2]; small_core<2>(lds, A, 1024, Bt + (size_t)rg * 1024, Bt + (size_t)(rg + 128) * 1024, 1024, o);
;         const int row = threadIdx.x >> 2, c4 = (threadIdx.x & 3) * 4, b = 16 + (row >> 4);
;         const float rstd = __builtin_amdgcn_rsqf(ssq[NP + row] * (1.0f / 1024.0f) + EPS);
;         const f32x4 g = o[0] * rstd + *(const f32x4*)(biasw + (size_t)b * 5632 + rg + c4), uu = o[1] * rstd + *(const f32x4*)(biasw + (size_t)b * 5632 + rg + 128 + c4);
;         u32x2 wv; wv.x = pk2(silu_f(g[0]) * uu[0], silu_f(g[1]) * uu[1]); wv.y = pk2(silu_f(g[2]) * uu[2], silu_f(g[3]) * uu[3]);
;         *(u32x2*)(ACT + (size_t)(NP + row) * DFF + j0 + c4) = wv;
;     }
; }
.LBB0_1062:
	s_cmpk_gt_u32 s4, 0x57
	s_cbranch_scc1 .LBB0_1064
	s_lshl_b32 s4, s4, 6
	v_lshl_add_u64 v[48:49], v[48:49], 0, s[4:5]
	global_load_dwordx4 v[126:129], v[48:49], off
	v_lshl_add_u64 v[46:47], v[46:47], 0, s[4:5]
	global_load_dwordx4 v[130:133], v[46:47], off
	v_add_co_u32_e32 v56, vcc, 0x16000, v46
	v_addc_co_u32_e32 v57, vcc, 0, v47, vcc
	v_add_co_u32_e32 v60, vcc, 0x2c000, v46
	s_nop 1
	v_addc_co_u32_e32 v61, vcc, 0, v47, vcc
	v_add_co_u32_e32 v68, vcc, 0x42000, v46
	global_load_dwordx4 v[142:145], v[56:57], off
	s_nop 0
	v_addc_co_u32_e32 v69, vcc, 0, v47, vcc
	v_add_co_u32_e32 v72, vcc, 0x58000, v46
	v_addc_co_u32_e32 v73, vcc, 0, v47, vcc
	v_add_co_u32_e32 v72, vcc, 0x6e000, v46
	s_nop 0
	v_addc_co_u32_e32 v73, vcc, 0, v47, vcc
	v_add_co_u32_e32 v60, vcc, 0x84000, v46
	s_nop 0
	v_addc_co_u32_e32 v61, vcc, 0, v47, vcc
	v_add_co_u32_e32 v46, vcc, 0x9a000, v46
	s_nop 0
	v_addc_co_u32_e32 v47, vcc, 0, v47, vcc
	s_waitcnt vmcnt(0)
	v_mfma_f32_16x16x32_bf16 v[28:31], v[126:129], v[130:133], v[28:31]
	v_mfma_f32_16x16x32_bf16 v[24:27], v[126:129], v[142:145], v[24:27]
.LBB0_1064:
	s_lshl_b32 s4, s47, 13
	v_lshlrev_b32_e32 v32, 6, v66
	s_add_i32 s4, s4, 0
	v_add3_u32 v32, s4, v44, v32
	s_barrier
	ds_write_b128 v32, v[28:31]
	ds_write_b128 v32, v[24:27] offset:1024
	ds_write_b128 v32, v[20:23] offset:2048
	ds_write_b128 v32, v[16:19] offset:3072
	ds_write_b128 v32, v[12:15] offset:4096
	ds_write_b128 v32, v[8:11] offset:5120
	ds_write_b128 v32, v[4:7] offset:6144
	ds_write_b128 v32, v[0:3] offset:7168
	v_lshlrev_b32_e32 v0, 4, v65
	v_or_b32_e32 v44, s46, v64
	v_and_b32_e32 v1, 48, v0
	v_and_b32_e32 v0, 0xffffffc0, v0
	v_ashrrev_i32_e32 v45, 31, v44
	v_add3_u32 v28, 0, v1, v0
	v_lshl_add_u64 v[56:57], v[44:45], 1, v[34:35]
	v_lshlrev_b64 v[52:53], 2, v[44:45]
	s_waitcnt lgkmcnt(0)
	s_barrier
	ds_read_b128 v[0:3], v28
	ds_read_b128 v[4:7], v28 offset:8192
	ds_read_b128 v[8:11], v28 offset:16384
	ds_read_b128 v[12:15], v28 offset:24576
	ds_read_b128 v[16:19], v28 offset:32768
	ds_read_b128 v[20:23], v28 offset:40960
	ds_read_b128 v[24:27], v28 offset:49152
	ds_read_b128 v[28:31], v28 offset:57344
	s_waitcnt lgkmcnt(0)
	s_barrier
	v_readfirstlane_b32 s100, v178
	s_cmpk_gt_u32 s100, 0x7f
	s_cbranch_scc1 .LBB0_1058
	global_load_dwordx2 v[58:59], v[56:57], off
	v_lshl_add_u64 v[44:45], v[36:37], 0, v[52:53]
	v_lshl_add_u64 v[48:49], v[38:39], 0, v[52:53]
	global_load_dwordx4 v[44:47], v[44:45], off
	v_lshl_add_u64 v[52:53], v[40:41], 0, v[52:53]
	global_load_dwordx4 v[48:51], v[48:49], off
	v_pk_add_f32 v[0:1], v[0:1], 0 op_sel_hi:[1,0]
	global_load_dwordx4 v[52:55], v[52:53], off
	v_pk_add_f32 v[0:1], v[0:1], v[4:5]
	v_pk_add_f32 v[2:3], v[2:3], 0 op_sel_hi:[1,0]
	v_pk_add_f32 v[0:1], v[0:1], v[8:9]
	v_pk_add_f32 v[2:3], v[2:3], v[6:7]
	v_pk_add_f32 v[0:1], v[0:1], v[12:13]
	v_pk_add_f32 v[2:3], v[2:3], v[10:11]
	v_pk_add_f32 v[0:1], v[0:1], v[16:17]
	v_pk_add_f32 v[2:3], v[2:3], v[14:15]
	v_pk_add_f32 v[0:1], v[0:1], v[20:21]
	v_pk_add_f32 v[2:3], v[2:3], v[18:19]
	v_pk_add_f32 v[0:1], v[0:1], v[24:25]
	v_pk_add_f32 v[2:3], v[2:3], v[22:23]
	v_pk_add_f32 v[0:1], v[0:1], v[28:29]
	v_pk_add_f32 v[2:3], v[2:3], v[26:27]
	s_waitcnt vmcnt(3)
	v_lshlrev_b32_e32 v4, 16, v58
	v_and_b32_e32 v5, 0xffff0000, v58
	v_lshlrev_b32_e32 v6, 16, v59
	s_waitcnt vmcnt(2)
	v_pk_mul_f32 v[4:5], v[44:45], v[4:5]
	v_and_b32_e32 v7, 0xffff0000, v59
	s_waitcnt vmcnt(1)
	v_pk_mul_f32 v[10:11], v[48:49], 0.5 op_sel_hi:[1,0]
	v_pk_add_f32 v[2:3], v[2:3], v[30:31]
	v_pk_fma_f32 v[4:5], v[0:1], v[10:11], v[4:5]
	v_pk_mul_f32 v[6:7], v[46:47], v[6:7]
	v_pk_mul_f32 v[8:9], v[50:51], 0.5 op_sel_hi:[1,0]
	v_mul_f32_e32 v0, v5, v5
	v_pk_fma_f32 v[2:3], v[2:3], v[8:9], v[6:7]
	v_fmac_f32_e32 v0, v4, v4
	v_fmac_f32_e32 v0, v2, v2
	v_fmac_f32_e32 v0, v3, v3
	ds_bpermute_b32 v1, v181, v0
	s_waitcnt vmcnt(0)
	v_pk_mul_f32 v[2:3], v[54:55], v[2:3]
	v_pk_mul_f32 v[4:5], v[52:53], v[4:5]
	s_waitcnt lgkmcnt(0)
	v_add_f32_e32 v0, v0, v1
	ds_bpermute_b32 v1, v245, v0
	v_cvt_pk_bf16_f32 v4, v4, v5
	v_cvt_pk_bf16_f32 v5, v2, v3
	global_store_dwordx2 v[56:57], v[4:5], off
	s_and_saveexec_b64 s[52:53], s[0:1]
	s_cbranch_execz .LBB0_1058
	s_waitcnt lgkmcnt(0)
	v_add_f32_e32 v0, v0, v1
	global_atomic_add_f32 v[42:43], v0, off
	s_branch .LBB0_1058

; #define LAS __attribute__((address_space(3)))
; __device__ __forceinline__ void small_resid(LAS unsigned char* lds, const bf16_t* A, int K, const bf16_t* Bt, const float* xs_in, float* X, const float* modp, float coef, ...
;     for (int un = c; un < 64; un += G) {
;         f32x4 o[1]; small_core<1>(lds, A, K, Bt + (size_t)(16 * un) * K, Bt, K, o);
;         const int row = threadIdx.x >> 2, col = 16 * un + (threadIdx.x & 3) * 4, b = 16 + (row >> 4);
;         f32x4 bs;
;         if (xs_in) bs = *(const f32x4*)(xs_in + (size_t)row * DM + col);
;         else { const u32x2 r_ = *(const u32x2*)(An + (size_t)(NP + row) * DM + col); const f32x4 rg = *(const f32x4*)(rgs + (size_t)b * 1024 + col);
.LBB0_1240:
	s_or_b64 exec, exec, s[0:1]
	s_add_u32 s3, s92, 0x38b0000
	s_addc_u32 s25, s93, 0
	s_add_u32 s22, s92, 0xda000
	s_addc_u32 s23, s93, 0
	s_add_u32 s34, s92, 0x1e2f0000
	s_addc_u32 s35, s93, 0
	s_add_u32 s36, s92, 0x1e86fc00
	s_addc_u32 s37, s93, 0
	s_and_b64 vcc, exec, s[6:7]
	s_waitcnt lgkmcnt(0)
	s_barrier
	s_and_b32 s99, s2, 3
	s_mov_b32 s101, 0
	v_lshlrev_b32_e32 v0, 9, v178
	v_and_b32_e32 v32, 0x7f800, v0
	v_mov_b32_e32 v33, 0
	v_or_b32_e32 v2, 16, v179
	v_lshl_add_u32 v2, s99, 1, v2
	v_lshl_add_u64 v[0:1], s[42:43], 0, v[32:33]
	s_mov_b64 s[0:1], 0x4000000
	v_lshl_add_u64 v[34:35], v[0:1], 0, s[0:1]
	s_lshl_b32 s100, s99, 16
	v_lshl_add_u64 v[34:35], v[34:35], 0, s[100:101]
	v_lshlrev_b32_e32 v32, 12, v2
	s_mov_b32 s0, 0x9000
	v_mov_b64_e32 v[0:1], s[22:23]
	v_lshl_add_u64 v[36:37], s[36:37], 0, v[32:33]
	v_mad_u64_u32 v[38:39], s[0:1], v2, s0, v[0:1]
	v_lshl_add_u64 v[40:41], s[34:35], 0, v[32:33]
	v_and_b32_e32 v0, 3, v178
	v_and_b32_e32 v32, 0x3fc, v178
	v_cmp_eq_u32_e64 s[0:1], 0, v0
	v_lshl_add_u64 v[0:1], s[92:93], 0, v[32:33]
	s_mov_b64 s[12:13], 0x1e7e7000
	v_readlane_b32 s58, v255, 2
	s_waitcnt vmcnt(1)
	v_and_b32_e32 v64, 12, v239
	s_mov_b32 s5, 0
	v_lshl_add_u64 v[42:43], v[0:1], 0, s[12:13]
	s_lshl_b32 s100, s99, 7
	v_lshl_add_u64 v[42:43], v[42:43], 0, s[100:101]
	s_mov_b64 s[12:13], 0x16000
	s_mov_b64 s[14:15], 0x2c000
	s_mov_b64 s[16:17], 0x42000
	s_mov_b64 s[18:19], 0x58000
	s_mov_b64 s[20:21], 0x6e000
	s_mov_b64 s[38:39], 0x84000
	s_mov_b64 s[40:41], 0x9a000
	s_lshr_b32 s33, s2, 2
	v_readlane_b32 s59, v255, 3
	s_branch .LBB0_1243

; #define LAS __attribute__((address_space(3)))
; __device__ __forceinline__ void small_resid(LAS unsigned char* lds, const bf16_t* A, int K, const bf16_t* Bt, const float* xs_in, float* X, const float* modp, float coef, ...
;     for (int un = c; un < 64; un += G) {
;         f32x4 o[1]; small_core<1>(lds, A, K, Bt + (size_t)(16 * un) * K, Bt, K, o);
;         const int row = threadIdx.x >> 2, col = 16 * un + (threadIdx.x & 3) * 4, b = 16 + (row >> 4);
;         f32x4 bs;
;         if (xs_in) bs = *(const f32x4*)(xs_in + (size_t)row * DM + col);
;         else { const u32x2 r_ = *(const u32x2*)(An + (size_t)(NP + row) * DM + col); const f32x4 rg = *(const f32x4*)(rgs + (size_t)b * 1024 + col);
.LBB0_1781:
	s_or_b64 exec, exec, s[0:1]
	s_add_u32 s3, s92, 0x3e30000
	s_addc_u32 s25, s93, 0
	s_add_u32 s4, s92, 0xe0000
	s_addc_u32 s5, s93, 0
	s_add_u32 s16, s92, 0x1e320000
	s_addc_u32 s17, s93, 0
	s_add_u32 s18, s92, 0x1e89fc00
	s_addc_u32 s19, s93, 0
	s_and_b64 vcc, exec, s[6:7]
	s_waitcnt lgkmcnt(0)
	s_barrier
	s_and_b32 s99, s2, 3
	s_mov_b32 s101, 0
	v_lshlrev_b32_e32 v0, 9, v178
	v_and_b32_e32 v32, 0x7f800, v0
	v_mov_b32_e32 v33, 0
	v_or_b32_e32 v2, 16, v179
	v_lshl_add_u32 v2, s99, 1, v2
	v_lshl_add_u64 v[0:1], s[42:43], 0, v[32:33]
	s_mov_b64 s[0:1], 0x4000000
	s_waitcnt vmcnt(1)
	v_lshl_add_u64 v[34:35], v[0:1], 0, s[0:1]
	s_lshl_b32 s100, s99, 16
	v_lshl_add_u64 v[34:35], v[34:35], 0, s[100:101]
	v_lshlrev_b32_e32 v32, 12, v2
	s_mov_b32 s0, 0x9000
	v_mov_b64_e32 v[0:1], s[4:5]
	v_lshl_add_u64 v[36:37], s[18:19], 0, v[32:33]
	s_waitcnt vmcnt(0)
	v_mad_u64_u32 v[38:39], s[0:1], v2, s0, v[0:1]
	v_lshl_add_u64 v[40:41], s[16:17], 0, v[32:33]
	v_and_b32_e32 v0, 3, v178
	v_and_b32_e32 v32, 0x3fc, v178
	v_cmp_eq_u32_e64 s[0:1], 0, v0
	v_lshl_add_u64 v[0:1], s[92:93], 0, v[32:33]
	s_mov_b64 s[8:9], 0x1e827800
	s_mov_b32 s7, 0
	v_lshl_add_u64 v[42:43], v[0:1], 0, s[8:9]
	s_lshl_b32 s100, s99, 7
	v_lshl_add_u64 v[42:43], v[42:43], 0, s[100:101]
	s_mov_b64 s[8:9], 0x16000
	s_mov_b64 s[10:11], 0x2c000
	s_mov_b64 s[12:13], 0x42000
	s_mov_b64 s[14:15], 0x58000
	s_mov_b64 s[20:21], 0x6e000
	s_mov_b64 s[22:23], 0x84000
	s_mov_b64 s[26:27], 0x9a000
	s_lshr_b32 s30, s2, 2
	s_branch .LBB0_1784

; #define LAS __attribute__((address_space(3)))
; template <int NB>
; __device__ __forceinline__ void small_core(LAS unsigned char* lds, const bf16_t* A, int lda, const bf16_t* B0, const bf16_t* B1, int K, f32x4 (&out)[NB]) {
;     int tid_ = threadIdx.x; asm volatile("" : "+v"(tid_));
;     const int tid = tid_, lane = tid & 63, w = __builtin_amdgcn_readfirstlane(tid >> 6), fr = lane & 15, fq = lane >> 4;
;     f32x4 acc[NB][8];
; #pragma unroll
;     for (int nb = 0; nb < NB; ++nb)
; #pragma unroll
;         for (int mb = 0; mb < 8; ++mb) acc[nb][mb] = (f32x4){0.f, 0.f, 0.f, 0.f};
;     const bf16_t* ap = A + (size_t)fr * lda + 8 * fq;
;     const bf16_t* bp0 = B0 + (size_t)fr * K + 8 * fq;
;     const bf16_t* bp1 = B1 + (size_t)fr * K + 8 * fq;
;     const int nsteps = K >> 5;
;     int st = w;
;     for (; st + 8 < nsteps; st += 16) {
;         const int k = st * 32, k2 = k + 256;
;         bf16x8 b[NB], b2[NB]; b[0] = *(const bf16x8*)(bp0 + k); b2[0] = *(const bf16x8*)(bp0 + k2);
;         if (NB == 2) { b[NB - 1] = *(const bf16x8*)(bp1 + k); b2[NB - 1] = *(const bf16x8*)(bp1 + k2); }
;         bf16x8 a[8], a2[8];
; #pragma unroll
;         for (int mb = 0; mb < 8; ++mb) { a[mb] = *(const bf16x8*)(ap + (size_t)(16 * mb) * lda + k); a2[mb] = *(const bf16x8*)(ap + (size_t)(16 * mb) * lda + k2); }
; #pragma unroll
;         for (int mb = 0; mb < 8; ++mb)
; #pragma unroll
;             for (int nb = 0; nb < NB; ++nb) { acc[nb][mb] = __builtin_amdgcn_mfma_f32_16x16x32_bf16(b[nb], a[mb], acc[nb][mb], 0, 0, 0);
;                 acc[nb][mb] = __builtin_amdgcn_mfma_f32_16x16x32_bf16(b2[nb], a2[mb], acc[nb][mb], 0, 0, 0); }
;     }
.LBB0_1784:
	v_mov_b32_e32 v64, v178
	s_lshl_b32 s31, s30, 4
	v_and_b32_e32 v65, 15, v64
	s_mul_i32 s6, s30, 0x16000
	v_mul_u32_u24_e32 v0, 0xb00, v65
	s_mul_hi_i32 s29, s31, 0x1600
	s_add_u32 s28, s3, s6
	v_bfe_u32 v2, v64, 4, 2
	v_lshlrev_b32_e32 v32, 1, v0
	s_addc_u32 s29, s25, s29
	v_readfirstlane_b32 s6, v64
	s_waitcnt lgkmcnt(0)
	v_lshl_add_u64 v[0:1], s[80:81], 0, v[32:33]
	v_lshlrev_b32_e32 v44, 4, v2
	v_mov_b32_e32 v45, v33
	s_ashr_i32 s33, s6, 6
	v_lshl_add_u64 v[46:47], v[0:1], 0, v[44:45]
	s_mul_i32 s100, s99, 0x2c000
	v_lshl_add_u64 v[46:47], v[46:47], 0, s[100:101]
	v_lshl_add_u64 v[0:1], s[28:29], 0, v[32:33]
	v_lshl_add_u64 v[48:49], v[0:1], 0, v[44:45]
	s_cmpk_gt_i32 s33, 0x4f
	v_mov_b32_e32 v3, 0
	v_mov_b32_e32 v2, 0
	v_mov_b32_e32 v1, 0
	v_mov_b32_e32 v0, 0
	v_mov_b32_e32 v7, 0
	v_mov_b32_e32 v6, 0
	v_mov_b32_e32 v5, 0
	v_mov_b32_e32 v4, 0
	v_mov_b32_e32 v11, 0
	v_mov_b32_e32 v10, 0
	v_mov_b32_e32 v9, 0
	v_mov_b32_e32 v8, 0
	v_mov_b32_e32 v15, 0
	v_mov_b32_e32 v14, 0
	v_mov_b32_e32 v13, 0
	v_mov_b32_e32 v12, 0
	v_mov_b32_e32 v19, 0
	v_mov_b32_e32 v18, 0
	v_mov_b32_e32 v17, 0
	v_mov_b32_e32 v16, 0
	v_mov_b32_e32 v23, 0
	v_mov_b32_e32 v22, 0
	v_mov_b32_e32 v21, 0
	v_mov_b32_e32 v20, 0
	v_mov_b32_e32 v27, 0
	v_mov_b32_e32 v26, 0
	v_mov_b32_e32 v25, 0
	v_mov_b32_e32 v24, 0
	v_mov_b32_e32 v31, 0
	v_mov_b32_e32 v30, 0
	v_mov_b32_e32 v29, 0
	v_mov_b32_e32 v28, 0
	s_mov_b32 s6, s33
	s_cbranch_scc1 .LBB0_1787
	v_mov_b32_e32 v28, 0
	v_lshl_add_u64 v[50:51], v[46:47], 0, s[8:9]
	v_lshl_add_u64 v[52:53], v[46:47], 0, s[10:11]
	v_lshl_add_u64 v[54:55], v[46:47], 0, s[12:13]
	v_lshl_add_u64 v[56:57], v[46:47], 0, s[14:15]
	v_lshl_add_u64 v[58:59], v[46:47], 0, s[20:21]
	v_lshl_add_u64 v[60:61], v[46:47], 0, s[22:23]
	v_lshl_add_u64 v[62:63], v[46:47], 0, s[26:27]
	s_lshl_b32 s28, s33, 5
	s_mov_b32 s6, s33
	v_mov_b32_e32 v29, v28
	v_mov_b32_e32 v30, v28
	v_mov_b32_e32 v31, v28
	v_mov_b32_e32 v24, v28
	v_mov_b32_e32 v25, v28
	v_mov_b32_e32 v26, v28
	v_mov_b32_e32 v27, v28
	v_mov_b32_e32 v20, v28
	v_mov_b32_e32 v21, v28
	v_mov_b32_e32 v22, v28
	v_mov_b32_e32 v23, v28
	v_mov_b32_e32 v16, v28
	v_mov_b32_e32 v17, v28
	v_mov_b32_e32 v18, v28
	v_mov_b32_e32 v19, v28
	v_mov_b32_e32 v12, v28
	v_mov_b32_e32 v13, v28
	v_mov_b32_e32 v14, v28
	v_mov_b32_e32 v15, v28
	v_mov_b32_e32 v8, v28
	v_mov_b32_e32 v9, v28
	v_mov_b32_e32 v10, v28
	v_mov_b32_e32 v11, v28
	v_mov_b32_e32 v4, v28
	v_mov_b32_e32 v5, v28
	v_mov_b32_e32 v6, v28
	v_mov_b32_e32 v7, v28
	v_mov_b32_e32 v0, v28
	v_mov_b32_e32 v1, v28
	v_mov_b32_e32 v2, v28
	v_mov_b32_e32 v3, v28
.LBB0_1786:
	s_ashr_i32 s29, s28, 31
	s_lshl_b64 s[34:35], s[28:29], 1
	v_lshl_add_u64 v[98:99], v[48:49], 0, s[34:35]
	v_lshl_add_u64 v[106:107], v[46:47], 0, s[34:35]
	v_lshl_add_u64 v[110:111], v[50:51], 0, s[34:35]
	v_lshl_add_u64 v[112:113], v[52:53], 0, s[34:35]
	v_lshl_add_u64 v[114:115], v[54:55], 0, s[34:35]
	v_lshl_add_u64 v[116:117], v[56:57], 0, s[34:35]
	v_lshl_add_u64 v[118:119], v[58:59], 0, s[34:35]
	v_lshl_add_u64 v[120:121], v[60:61], 0, s[34:35]
	v_lshl_add_u64 v[122:123], v[62:63], 0, s[34:35]
	global_load_dwordx4 v[124:127], v[98:99], off
	global_load_dwordx4 v[128:131], v[106:107], off
	global_load_dwordx4 v[132:135], v[110:111], off
	s_nop 0
	global_load_dwordx4 v[156:159], v[98:99], off offset:512
	s_nop 0
	s_nop 0
	global_load_dwordx4 v[164:167], v[106:107], off offset:512
	s_mov_b32 s29, s6
	s_add_i32 s6, s6, 16
	s_addk_i32 s28, 0x200
	s_cmp_lt_i32 s29, 64
	global_load_dwordx4 v[168:171], v[110:111], off offset:512
	s_waitcnt vmcnt(0)
	v_mfma_f32_16x16x32_bf16 v[28:31], v[124:127], v[128:131], v[28:31]
	v_mfma_f32_16x16x32_bf16 v[24:27], v[124:127], v[132:135], v[24:27]
	v_mfma_f32_16x16x32_bf16 v[28:31], v[156:159], v[164:167], v[28:31]
	v_mfma_f32_16x16x32_bf16 v[24:27], v[156:159], v[168:171], v[24:27]
	s_cbranch_scc1 .LBB0_1786
; #define LAS __attribute__((address_space(3)))
; template <int NB>
; __device__ __forceinline__ void small_core(LAS unsigned char* lds, const bf16_t* A, int lda, const bf16_t* B0, const bf16_t* B1, int K, f32x4 (&out)[NB]) {
;     ...
;     if (st < nsteps) {
;         const int k = st * 32;
;         bf16x8 b[NB]; b[0] = *(const bf16x8*)(bp0 + k); if (NB == 2) b[NB - 1] = *(const bf16x8*)(bp1 + k);
;         bf16x8 a[8];
; #pragma unroll
;         for (int mb = 0; mb < 8; ++mb) a[mb] = *(const bf16x8*)(ap + (size_t)(16 * mb) * lda + k);
; #pragma unroll
;         for (int mb = 0; mb < 8; ++mb)
; #pragma unroll
;             for (int nb = 0; nb < NB; ++nb) acc[nb][mb] = __builtin_amdgcn_mfma_f32_16x16x32_bf16(b[nb], a[mb], acc[nb][mb], 0, 0, 0);
;     }
;     LAS float* red = (LAS float*)lds;
;     __syncthreads();
; #pragma unroll
;     for (int nb = 0; nb < NB; ++nb)
; #pragma unroll
;         for (int mb = 0; mb < 8; ++mb) *(LAS f32x4*)(red + ((w * 128 + 16 * mb + fr) * (16 * NB) + nb * 16 + 4 * fq)) = acc[nb][mb];
;     __syncthreads();
;     const int row = tid >> 2, c4 = (tid & 3) * 4;
; #pragma unroll
;     for (int nb = 0; nb < NB; ++nb) { f32x4 s = (f32x4){0.f, 0.f, 0.f, 0.f};
; #pragma unroll
;         for (int w8 = 0; w8 < 8; ++w8) s += *(const LAS f32x4*)(red + ((w8 * 128 + row) * (16 * NB) + nb * 16 + c4));
;         out[nb] = s; }
;     __syncthreads();
; }
; __device__ __forceinline__ void small_swiglu(LAS unsigned char* lds, const bf16_t* A, const bf16_t* Bt, bf16_t* ACT, const float* ssq, const float* biasw, int G, int c) {
;     for (int un = c; un < DFF / 16; un += G) {
;         const int j0 = 16 * un, rg = (j0 >> 7) * 256 + (j0 & 127);
;         f32x4 o[2]; small_core<2>(lds, A, 1024, Bt + (size_t)rg * 1024, Bt + (size_t)(rg + 128) * 1024, 1024, o);
;         const int row = threadIdx.x >> 2, c4 = (threadIdx.x & 3) * 4, b = 16 + (row >> 4);
;         const float rstd = __builtin_amdgcn_rsqf(ssq[NP + row] * (1.0f / 1024.0f) + EPS);
;         const f32x4 g = o[0] * rstd + *(const f32x4*)(biasw + (size_t)b * 5632 + rg + c4), uu = o[1] * rstd + *(const f32x4*)(biasw + (size_t)b * 5632 + rg + 128 + c4);
;         u32x2 wv; wv.x = pk2(silu_f(g[0]) * uu[0], silu_f(g[1]) * uu[1]); wv.y = pk2(silu_f(g[2]) * uu[2], silu_f(g[3]) * uu[3]);
;         *(u32x2*)(ACT + (size_t)(NP + row) * DFF + j0 + c4) = wv;
;     }
; }
.LBB0_1787:
	s_cmpk_gt_u32 s6, 0x57
	s_cbranch_scc1 .LBB0_1789
	s_lshl_b32 s6, s6, 6
	v_lshl_add_u64 v[48:49], v[48:49], 0, s[6:7]
	global_load_dwordx4 v[124:127], v[48:49], off
	v_lshl_add_u64 v[46:47], v[46:47], 0, s[6:7]
	global_load_dwordx4 v[128:131], v[46:47], off
	v_add_co_u32_e32 v56, vcc, 0x16000, v46
	v_addc_co_u32_e32 v57, vcc, 0, v47, vcc
	v_add_co_u32_e32 v60, vcc, 0x2c000, v46
	s_nop 1
	v_addc_co_u32_e32 v61, vcc, 0, v47, vcc
	v_add_co_u32_e32 v66, vcc, 0x42000, v46
	global_load_dwordx4 v[132:135], v[56:57], off
	s_nop 0
	v_addc_co_u32_e32 v67, vcc, 0, v47, vcc
	v_add_co_u32_e32 v70, vcc, 0x58000, v46
	v_addc_co_u32_e32 v71, vcc, 0, v47, vcc
	v_add_co_u32_e32 v70, vcc, 0x6e000, v46
	s_nop 0
	v_addc_co_u32_e32 v71, vcc, 0, v47, vcc
	v_add_co_u32_e32 v60, vcc, 0x84000, v46
	s_nop 0
	v_addc_co_u32_e32 v61, vcc, 0, v47, vcc
	v_add_co_u32_e32 v46, vcc, 0x9a000, v46
	s_nop 0
	v_addc_co_u32_e32 v47, vcc, 0, v47, vcc
	s_waitcnt vmcnt(0)
	v_mfma_f32_16x16x32_bf16 v[28:31], v[124:127], v[128:131], v[28:31]
	v_mfma_f32_16x16x32_bf16 v[24:27], v[124:127], v[132:135], v[24:27]
.LBB0_1789:
	s_lshl_b32 s6, s33, 13
	v_lshlrev_b32_e32 v32, 6, v65
	s_add_i32 s6, s6, 0
	v_add3_u32 v32, s6, v44, v32
	s_barrier
	ds_write_b128 v32, v[28:31]
	ds_write_b128 v32, v[24:27] offset:1024
	ds_write_b128 v32, v[20:23] offset:2048
	ds_write_b128 v32, v[16:19] offset:3072
	ds_write_b128 v32, v[12:15] offset:4096
	ds_write_b128 v32, v[8:11] offset:5120
	ds_write_b128 v32, v[4:7] offset:6144
	ds_write_b128 v32, v[0:3] offset:7168
	v_lshlrev_b32_e32 v0, 4, v64
	v_or_b32_e32 v44, s31, v228
	v_and_b32_e32 v1, 48, v0
	v_and_b32_e32 v0, 0xffffffc0, v0
	v_ashrrev_i32_e32 v45, 31, v44
	v_add3_u32 v28, 0, v1, v0
	v_lshl_add_u64 v[56:57], v[44:45], 1, v[34:35]
	v_lshlrev_b64 v[52:53], 2, v[44:45]
	s_waitcnt lgkmcnt(0)
	s_barrier
	ds_read_b128 v[0:3], v28
	ds_read_b128 v[4:7], v28 offset:8192
	ds_read_b128 v[8:11], v28 offset:16384
	ds_read_b128 v[12:15], v28 offset:24576
	ds_read_b128 v[16:19], v28 offset:32768
	ds_read_b128 v[20:23], v28 offset:40960
	ds_read_b128 v[24:27], v28 offset:49152
	ds_read_b128 v[28:31], v28 offset:57344
	s_waitcnt lgkmcnt(0)
	s_barrier
	v_readfirstlane_b32 s100, v178
	s_cmpk_gt_u32 s100, 0x7f
	s_cbranch_scc1 .LBB0_1783
	global_load_dwordx2 v[58:59], v[56:57], off
	v_lshl_add_u64 v[44:45], v[36:37], 0, v[52:53]
	v_lshl_add_u64 v[48:49], v[38:39], 0, v[52:53]
	global_load_dwordx4 v[44:47], v[44:45], off
	v_lshl_add_u64 v[52:53], v[40:41], 0, v[52:53]
	global_load_dwordx4 v[48:51], v[48:49], off
	v_pk_add_f32 v[0:1], v[0:1], 0 op_sel_hi:[1,0]
	global_load_dwordx4 v[52:55], v[52:53], off
	v_pk_add_f32 v[0:1], v[0:1], v[4:5]
	v_pk_add_f32 v[2:3], v[2:3], 0 op_sel_hi:[1,0]
	v_pk_add_f32 v[0:1], v[0:1], v[8:9]
	v_pk_add_f32 v[2:3], v[2:3], v[6:7]
	v_pk_add_f32 v[0:1], v[0:1], v[12:13]
	v_pk_add_f32 v[2:3], v[2:3], v[10:11]
	v_pk_add_f32 v[0:1], v[0:1], v[16:17]
	v_pk_add_f32 v[2:3], v[2:3], v[14:15]
	v_pk_add_f32 v[0:1], v[0:1], v[20:21]
	v_pk_add_f32 v[2:3], v[2:3], v[18:19]
	v_pk_add_f32 v[0:1], v[0:1], v[24:25]
	v_pk_add_f32 v[2:3], v[2:3], v[22:23]
	v_pk_add_f32 v[0:1], v[0:1], v[28:29]
	v_pk_add_f32 v[2:3], v[2:3], v[26:27]
	s_waitcnt vmcnt(3)
	v_lshlrev_b32_e32 v4, 16, v58
	v_and_b32_e32 v5, 0xffff0000, v58
	v_lshlrev_b32_e32 v6, 16, v59
	s_waitcnt vmcnt(2)
	v_pk_mul_f32 v[4:5], v[44:45], v[4:5]
	v_and_b32_e32 v7, 0xffff0000, v59
	s_waitcnt vmcnt(1)
	v_pk_mul_f32 v[10:11], v[48:49], 0.5 op_sel_hi:[1,0]
	v_pk_add_f32 v[2:3], v[2:3], v[30:31]
	v_pk_fma_f32 v[4:5], v[0:1], v[10:11], v[4:5]
	v_pk_mul_f32 v[6:7], v[46:47], v[6:7]
	v_pk_mul_f32 v[8:9], v[50:51], 0.5 op_sel_hi:[1,0]
	v_mul_f32_e32 v0, v5, v5
	v_pk_fma_f32 v[2:3], v[2:3], v[8:9], v[6:7]
	v_fmac_f32_e32 v0, v4, v4
	v_fmac_f32_e32 v0, v2, v2
	v_fmac_f32_e32 v0, v3, v3
	ds_bpermute_b32 v1, v181, v0
	s_waitcnt vmcnt(0)
	v_pk_mul_f32 v[2:3], v[54:55], v[2:3]
	v_pk_mul_f32 v[4:5], v[52:53], v[4:5]
	s_waitcnt lgkmcnt(0)
	v_add_f32_e32 v0, v0, v1
	ds_bpermute_b32 v1, v245, v0
	v_cvt_pk_bf16_f32 v4, v4, v5
	v_cvt_pk_bf16_f32 v5, v2, v3
	global_store_dwordx2 v[56:57], v[4:5], off
	s_and_saveexec_b64 s[28:29], s[0:1]
	s_cbranch_execz .LBB0_1783
	s_waitcnt lgkmcnt(0)
	v_add_f32_e32 v0, v0, v1
	global_atomic_add_f32 v[42:43], v0, off
	s_branch .LBB0_1783
